# grid barrier: follower workgroups poll the top-level generation word directly instead of the per-XCD relay word (leader no longer bumps the relay)
# baseline (speedup 1.0000x reference)
.LBB0_25:
	s_or_b64 exec, exec, s[10:11]
	v_cvt_f32_u32_e32 v5, v3
	s_waitcnt vmcnt(0)
	v_readfirstlane_b32 s8, v4
	v_sub_u32_e32 v4, 0, v3
	v_rcp_iflag_f32_e32 v5, v5
	v_add_u32_e32 v6, s8, v2
	v_mul_f32_e32 v5, 0x4f7ffffe, v5
	v_cvt_u32_f32_e32 v5, v5
	v_mul_lo_u32 v2, v4, v5
	v_mul_hi_u32 v2, v5, v2
	v_add_u32_e32 v2, v5, v2
	v_mul_hi_u32 v2, v6, v2
	v_mul_lo_u32 v4, v2, v3
	v_sub_u32_e32 v4, v6, v4
	v_add_u32_e32 v5, 1, v2
	v_sub_u32_e32 v7, v4, v3
	v_cmp_ge_u32_e32 vcc, v4, v3
	s_nop 1
	v_cndmask_b32_e32 v2, v2, v5, vcc
	v_cndmask_b32_e32 v4, v4, v7, vcc
	v_add_u32_e32 v5, 1, v2
	v_cmp_ge_u32_e32 vcc, v4, v3
	v_add_u32_e32 v4, 1, v6
	s_nop 0
	v_cndmask_b32_e32 v2, v2, v5, vcc
	v_mul_lo_u32 v5, v3, v2
	v_add_u32_e32 v3, v5, v3
	v_cmp_ne_u32_e32 vcc, v4, v3
	s_and_saveexec_b64 s[8:9], vcc
	s_xor_b64 s[8:9], exec, s[8:9]
	s_cbranch_execz .LBB0_39
	s_waitcnt lgkmcnt(0)
	v_mov_b32_e32 v1, 0x3500
	global_load_dword v1, v1, s[92:93] sc1
	s_add_u32 s12, s92, 0x3500
	s_addc_u32 s13, s93, 0
	s_waitcnt vmcnt(0)
	v_cmp_eq_u32_e32 vcc, v1, v2
	s_and_saveexec_b64 s[10:11], vcc
	s_cbranch_execz .LBB0_38
	s_mov_b32 s24, 1
	s_mov_b64 s[14:15], 0
	v_mov_b32_e32 v1, 0
	s_branch .LBB0_29

.LBB0_56:
	s_or_b64 exec, exec, s[8:9]
	s_mov_b64 s[8:9], exec
	v_mbcnt_lo_u32_b32 v1, s8, 0
	v_mbcnt_hi_u32_b32 v1, s9, v1
	v_cmp_eq_u32_e32 vcc, 0, v1
	s_waitcnt vmcnt(0)
	buffer_inv sc1
	s_and_saveexec_b64 s[10:11], vcc
	s_cbranch_execz .LBB0_58
	s_bcnt1_i32_b64 s8, s[8:9]
	v_mov_b32_e32 v1, 0x2000
	v_mov_b32_e32 v2, s8
	s_nop 0

.LBB0_167:
	s_or_b64 exec, exec, s[8:9]
	v_cvt_f32_u32_e32 v5, v3
	s_waitcnt vmcnt(0)
	v_readfirstlane_b32 s6, v4
	v_sub_u32_e32 v4, 0, v3
	v_rcp_iflag_f32_e32 v5, v5
	v_add_u32_e32 v6, s6, v2
	v_mul_f32_e32 v5, 0x4f7ffffe, v5
	v_cvt_u32_f32_e32 v5, v5
	v_mul_lo_u32 v2, v4, v5
	v_mul_hi_u32 v2, v5, v2
	v_add_u32_e32 v2, v5, v2
	v_mul_hi_u32 v2, v6, v2
	v_mul_lo_u32 v4, v2, v3
	v_sub_u32_e32 v4, v6, v4
	v_add_u32_e32 v5, 1, v2
	v_sub_u32_e32 v7, v4, v3
	v_cmp_ge_u32_e32 vcc, v4, v3
	s_nop 1
	v_cndmask_b32_e32 v2, v2, v5, vcc
	v_cndmask_b32_e32 v4, v4, v7, vcc
	v_add_u32_e32 v5, 1, v2
	v_cmp_ge_u32_e32 vcc, v4, v3
	v_add_u32_e32 v4, 1, v6
	s_nop 0
	v_cndmask_b32_e32 v2, v2, v5, vcc
	v_mul_lo_u32 v5, v3, v2
	v_add_u32_e32 v3, v5, v3
	v_cmp_ne_u32_e32 vcc, v4, v3
	s_and_saveexec_b64 s[6:7], vcc
	s_xor_b64 s[6:7], exec, s[6:7]
	s_cbranch_execz .LBB0_181
	s_waitcnt lgkmcnt(0)
	v_mov_b32_e32 v1, 0x3500
	global_load_dword v1, v1, s[92:93] sc1
	s_add_u32 s10, s92, 0x3500
	s_addc_u32 s11, s93, 0
	s_waitcnt vmcnt(0)
	v_cmp_eq_u32_e32 vcc, v1, v2
	s_and_saveexec_b64 s[8:9], vcc
	s_cbranch_execz .LBB0_180
	s_mov_b32 s22, 1
	s_mov_b64 s[12:13], 0
	v_mov_b32_e32 v1, 0
	s_branch .LBB0_171

.LBB0_198:
	s_or_b64 exec, exec, s[6:7]
	s_mov_b64 s[6:7], exec
	v_mbcnt_lo_u32_b32 v1, s6, 0
	v_mbcnt_hi_u32_b32 v1, s7, v1
	v_cmp_eq_u32_e32 vcc, 0, v1
	s_waitcnt vmcnt(0)
	buffer_inv sc1
	s_and_saveexec_b64 s[8:9], vcc
	s_cbranch_execz .LBB0_200
	s_bcnt1_i32_b64 s6, s[6:7]
	v_mov_b32_e32 v1, 0x2000
	v_mov_b32_e32 v2, s6
	s_nop 0

.LBB0_230:
	s_or_b64 exec, exec, s[6:7]
	v_cvt_f32_u32_e32 v5, v3
	s_waitcnt vmcnt(0)
	v_readfirstlane_b32 s4, v4
	v_sub_u32_e32 v4, 0, v3
	v_rcp_iflag_f32_e32 v5, v5
	v_add_u32_e32 v6, s4, v2
	v_mul_f32_e32 v5, 0x4f7ffffe, v5
	v_cvt_u32_f32_e32 v5, v5
	v_mul_lo_u32 v2, v4, v5
	v_mul_hi_u32 v2, v5, v2
	v_add_u32_e32 v2, v5, v2
	v_mul_hi_u32 v2, v6, v2
	v_mul_lo_u32 v4, v2, v3
	v_sub_u32_e32 v4, v6, v4
	v_add_u32_e32 v5, 1, v2
	v_sub_u32_e32 v7, v4, v3
	v_cmp_ge_u32_e32 vcc, v4, v3
	s_nop 1
	v_cndmask_b32_e32 v2, v2, v5, vcc
	v_cndmask_b32_e32 v4, v4, v7, vcc
	v_add_u32_e32 v5, 1, v2
	v_cmp_ge_u32_e32 vcc, v4, v3
	v_add_u32_e32 v4, 1, v6
	s_nop 0
	v_cndmask_b32_e32 v2, v2, v5, vcc
	v_mul_lo_u32 v5, v3, v2
	v_add_u32_e32 v3, v5, v3
	v_cmp_ne_u32_e32 vcc, v4, v3
	s_and_saveexec_b64 s[4:5], vcc
	s_xor_b64 s[4:5], exec, s[4:5]
	s_cbranch_execz .LBB0_244
	s_waitcnt lgkmcnt(0)
	v_mov_b32_e32 v1, 0x3500
	global_load_dword v1, v1, s[92:93] sc1
	s_add_u32 s8, s92, 0x3500
	s_addc_u32 s9, s93, 0
	s_waitcnt vmcnt(0)
	v_cmp_eq_u32_e32 vcc, v1, v2
	s_and_saveexec_b64 s[6:7], vcc
	s_cbranch_execz .LBB0_243
	s_mov_b32 s20, 1
	s_mov_b64 s[10:11], 0
	v_mov_b32_e32 v1, 0
	s_branch .LBB0_234

.LBB0_261:
	s_or_b64 exec, exec, s[4:5]
	s_mov_b64 s[4:5], exec
	v_mbcnt_lo_u32_b32 v1, s4, 0
	v_mbcnt_hi_u32_b32 v1, s5, v1
	v_cmp_eq_u32_e32 vcc, 0, v1
	s_waitcnt vmcnt(0)
	buffer_inv sc1
	s_and_saveexec_b64 s[6:7], vcc
	s_cbranch_execz .LBB0_263
	s_bcnt1_i32_b64 s4, s[4:5]
	v_mov_b32_e32 v1, 0x2000
	v_mov_b32_e32 v2, s4
	s_nop 0

.LBB0_412:
	s_or_b64 exec, exec, s[8:9]
	v_cvt_f32_u32_e32 v5, v3
	s_waitcnt vmcnt(0)
	v_readfirstlane_b32 s6, v4
	v_sub_u32_e32 v4, 0, v3
	v_rcp_iflag_f32_e32 v5, v5
	v_add_u32_e32 v6, s6, v1
	v_mul_f32_e32 v5, 0x4f7ffffe, v5
	v_cvt_u32_f32_e32 v5, v5
	v_mul_lo_u32 v1, v4, v5
	v_mul_hi_u32 v1, v5, v1
	v_add_u32_e32 v1, v5, v1
	v_mul_hi_u32 v1, v6, v1
	v_mul_lo_u32 v4, v1, v3
	v_sub_u32_e32 v4, v6, v4
	v_add_u32_e32 v5, 1, v1
	v_cmp_ge_u32_e32 vcc, v4, v3
	s_nop 1
	v_cndmask_b32_e32 v1, v1, v5, vcc
	v_sub_u32_e32 v5, v4, v3
	v_cndmask_b32_e32 v4, v4, v5, vcc
	v_add_u32_e32 v5, 1, v1
	v_cmp_ge_u32_e32 vcc, v4, v3
	v_add_u32_e32 v4, 1, v6
	s_nop 0
	v_cndmask_b32_e32 v1, v1, v5, vcc
	v_mul_lo_u32 v5, v3, v1
	v_add_u32_e32 v3, v5, v3
	v_cmp_ne_u32_e32 vcc, v4, v3
	s_and_saveexec_b64 s[6:7], vcc
	s_xor_b64 s[6:7], exec, s[6:7]
	s_cbranch_execz .LBB0_426
	s_waitcnt lgkmcnt(0)
	v_mov_b32_e32 v2, 0x3500
	global_load_dword v2, v2, s[92:93] sc1
	s_add_u32 s10, s92, 0x3500
	s_addc_u32 s11, s93, 0
	s_waitcnt vmcnt(0)
	v_cmp_eq_u32_e32 vcc, v2, v1
	s_and_saveexec_b64 s[8:9], vcc
	s_cbranch_execz .LBB0_425
	s_mov_b32 s22, 1
	s_mov_b64 s[12:13], 0
	v_mov_b32_e32 v2, 0
	s_branch .LBB0_416

.LBB0_476:
	s_or_b64 exec, exec, s[8:9]
	v_cvt_f32_u32_e32 v5, v3
	s_waitcnt vmcnt(0)
	v_readfirstlane_b32 s6, v4
	v_sub_u32_e32 v4, 0, v3
	v_rcp_iflag_f32_e32 v5, v5
	v_add_u32_e32 v6, s6, v2
	v_mul_f32_e32 v5, 0x4f7ffffe, v5
	v_cvt_u32_f32_e32 v5, v5
	v_mul_lo_u32 v2, v4, v5
	v_mul_hi_u32 v2, v5, v2
	v_add_u32_e32 v2, v5, v2
	v_mul_hi_u32 v2, v6, v2
	v_mul_lo_u32 v4, v2, v3
	v_sub_u32_e32 v4, v6, v4
	v_add_u32_e32 v5, 1, v2
	v_cmp_ge_u32_e32 vcc, v4, v3
	s_nop 1
	v_cndmask_b32_e32 v2, v2, v5, vcc
	v_sub_u32_e32 v5, v4, v3
	v_cndmask_b32_e32 v4, v4, v5, vcc
	v_add_u32_e32 v5, 1, v2
	v_cmp_ge_u32_e32 vcc, v4, v3
	v_add_u32_e32 v4, 1, v6
	s_nop 0
	v_cndmask_b32_e32 v2, v2, v5, vcc
	v_mul_lo_u32 v5, v3, v2
	v_add_u32_e32 v3, v5, v3
	v_cmp_ne_u32_e32 vcc, v4, v3
	s_and_saveexec_b64 s[6:7], vcc
	s_xor_b64 s[6:7], exec, s[6:7]
	s_cbranch_execz .LBB0_490
	s_waitcnt lgkmcnt(0)
	v_mov_b32_e32 v1, 0x3500
	global_load_dword v1, v1, s[92:93] sc1
	s_add_u32 s10, s92, 0x3500
	s_addc_u32 s11, s93, 0
	s_waitcnt vmcnt(0)
	v_cmp_eq_u32_e32 vcc, v1, v2
	s_and_saveexec_b64 s[8:9], vcc
	s_cbranch_execz .LBB0_489
	s_mov_b32 s22, 1
	s_mov_b64 s[12:13], 0
	v_mov_b32_e32 v1, 0
	s_branch .LBB0_480

.LBB0_600:
	s_or_b64 exec, exec, s[6:7]
	v_cvt_f32_u32_e32 v5, v3
	s_waitcnt vmcnt(0)
	v_readfirstlane_b32 s4, v4
	v_sub_u32_e32 v4, 0, v3
	v_rcp_iflag_f32_e32 v5, v5
	v_add_u32_e32 v6, s4, v2
	v_mul_f32_e32 v5, 0x4f7ffffe, v5
	v_cvt_u32_f32_e32 v5, v5
	v_mul_lo_u32 v2, v4, v5
	v_mul_hi_u32 v2, v5, v2
	v_add_u32_e32 v2, v5, v2
	v_mul_hi_u32 v2, v6, v2
	v_mul_lo_u32 v4, v2, v3
	v_sub_u32_e32 v4, v6, v4
	v_add_u32_e32 v5, 1, v2
	v_cmp_ge_u32_e32 vcc, v4, v3
	s_nop 1
	v_cndmask_b32_e32 v2, v2, v5, vcc
	v_sub_u32_e32 v5, v4, v3
	v_cndmask_b32_e32 v4, v4, v5, vcc
	v_add_u32_e32 v5, 1, v2
	v_cmp_ge_u32_e32 vcc, v4, v3
	v_add_u32_e32 v4, 1, v6
	s_nop 0
	v_cndmask_b32_e32 v2, v2, v5, vcc
	v_mul_lo_u32 v5, v3, v2
	v_add_u32_e32 v3, v5, v3
	v_cmp_ne_u32_e32 vcc, v4, v3
	s_and_saveexec_b64 s[4:5], vcc
	s_xor_b64 s[4:5], exec, s[4:5]
	s_cbranch_execz .LBB0_614
	s_waitcnt lgkmcnt(0)
	v_mov_b32_e32 v1, 0x3500
	global_load_dword v1, v1, s[92:93] sc1
	s_add_u32 s8, s92, 0x3500
	s_addc_u32 s9, s93, 0
	s_waitcnt vmcnt(0)
	v_cmp_eq_u32_e32 vcc, v1, v2
	s_and_saveexec_b64 s[6:7], vcc
	s_cbranch_execz .LBB0_613
	s_mov_b32 s22, 1
	s_mov_b64 s[10:11], 0
	v_mov_b32_e32 v1, 0
	s_branch .LBB0_604

.LBB0_860:
	s_or_b64 exec, exec, s[6:7]
	v_cvt_f32_u32_e32 v5, v3
	s_waitcnt vmcnt(0)
	v_readfirstlane_b32 s4, v4
	v_sub_u32_e32 v4, 0, v3
	v_rcp_iflag_f32_e32 v5, v5
	v_add_u32_e32 v6, s4, v2
	v_mul_f32_e32 v5, 0x4f7ffffe, v5
	v_cvt_u32_f32_e32 v5, v5
	v_mul_lo_u32 v2, v4, v5
	v_mul_hi_u32 v2, v5, v2
	v_add_u32_e32 v2, v5, v2
	v_mul_hi_u32 v2, v6, v2
	v_mul_lo_u32 v4, v2, v3
	v_sub_u32_e32 v4, v6, v4
	v_add_u32_e32 v5, 1, v2
	v_cmp_ge_u32_e32 vcc, v4, v3
	s_nop 1
	v_cndmask_b32_e32 v2, v2, v5, vcc
	v_sub_u32_e32 v5, v4, v3
	v_cndmask_b32_e32 v4, v4, v5, vcc
	v_add_u32_e32 v5, 1, v2
	v_cmp_ge_u32_e32 vcc, v4, v3
	v_add_u32_e32 v4, 1, v6
	s_nop 0
	v_cndmask_b32_e32 v2, v2, v5, vcc
	v_mul_lo_u32 v5, v3, v2
	v_add_u32_e32 v3, v5, v3
	v_cmp_ne_u32_e32 vcc, v4, v3
	s_and_saveexec_b64 s[4:5], vcc
	s_xor_b64 s[4:5], exec, s[4:5]
	s_cbranch_execz .LBB0_874
	s_waitcnt lgkmcnt(0)
	v_mov_b32_e32 v1, 0x3500
	global_load_dword v1, v1, s[92:93] sc1
	s_add_u32 s8, s92, 0x3500
	s_addc_u32 s9, s93, 0
	s_waitcnt vmcnt(0)
	v_cmp_eq_u32_e32 vcc, v1, v2
	s_and_saveexec_b64 s[6:7], vcc
	s_cbranch_execz .LBB0_873
	s_mov_b32 s20, 1
	s_mov_b64 s[10:11], 0
	v_mov_b32_e32 v1, 0
	s_branch .LBB0_864

.LBB0_919:
	s_or_b64 exec, exec, s[8:9]
	v_cvt_f32_u32_e32 v5, v3
	s_waitcnt vmcnt(0)
	v_readfirstlane_b32 s4, v4
	v_sub_u32_e32 v4, 0, v3
	v_rcp_iflag_f32_e32 v5, v5
	v_add_u32_e32 v6, s4, v2
	v_mul_f32_e32 v5, 0x4f7ffffe, v5
	v_cvt_u32_f32_e32 v5, v5
	v_mul_lo_u32 v2, v4, v5
	v_mul_hi_u32 v2, v5, v2
	v_add_u32_e32 v2, v5, v2
	v_mul_hi_u32 v2, v6, v2
	v_mul_lo_u32 v4, v2, v3
	v_sub_u32_e32 v4, v6, v4
	v_add_u32_e32 v5, 1, v2
	v_cmp_ge_u32_e32 vcc, v4, v3
	s_nop 1
	v_cndmask_b32_e32 v2, v2, v5, vcc
	v_sub_u32_e32 v5, v4, v3
	v_cndmask_b32_e32 v4, v4, v5, vcc
	v_add_u32_e32 v5, 1, v2
	v_cmp_ge_u32_e32 vcc, v4, v3
	v_add_u32_e32 v4, 1, v6
	s_nop 0
	v_cndmask_b32_e32 v2, v2, v5, vcc
	v_mul_lo_u32 v5, v3, v2
	v_add_u32_e32 v3, v5, v3
	v_cmp_ne_u32_e32 vcc, v4, v3
	s_and_saveexec_b64 s[4:5], vcc
	s_xor_b64 s[4:5], exec, s[4:5]
	s_cbranch_execz .LBB0_933
	s_waitcnt lgkmcnt(0)
	v_mov_b32_e32 v1, 0x3500
	global_load_dword v1, v1, s[92:93] sc1
	s_add_u32 s10, s92, 0x3500
	s_addc_u32 s11, s93, 0
	s_waitcnt vmcnt(0)
	v_cmp_eq_u32_e32 vcc, v1, v2
	s_and_saveexec_b64 s[8:9], vcc
	s_cbranch_execz .LBB0_932
	s_mov_b32 s22, 1
	s_mov_b64 s[12:13], 0
	v_mov_b32_e32 v1, 0
	s_branch .LBB0_923

.LBB0_950:
	s_or_b64 exec, exec, s[4:5]
	s_mov_b64 s[4:5], exec
	v_mbcnt_lo_u32_b32 v1, s4, 0
	v_mbcnt_hi_u32_b32 v1, s5, v1
	v_cmp_eq_u32_e32 vcc, 0, v1
	s_waitcnt vmcnt(0)
	buffer_inv sc1
	s_and_saveexec_b64 s[8:9], vcc
	s_cbranch_execz .LBB0_952
	s_bcnt1_i32_b64 s4, s[4:5]
	v_mov_b32_e32 v1, 0x2000
	v_mov_b32_e32 v2, s4
	s_nop 0
